# 192-row GEMM loops (out/down proj): waves 4-7 skip the LDS-DMA piece covering the unused A rows 96-127, counted vmcnt(6) for them
# speedup vs baseline: 1.0151x; 1.0151x over previous
; #define PG8_STAGE(bufoff, gbase, voff) do { _Pragma("unroll") for (int _i = 0; _i < 2; ++_i) \
;         __builtin_amdgcn_global_load_lds((const unsigned*)((const char*)(gbase) + (voff)[_i]), (LAS unsigned*)(lds + (bufoff) + ldsw + _i * 8192), 16, 0, 0); } while (0)
; #define PG8_LDA(dst, b, h) do { _Pragma("unroll") for (int m = 0; m < NM; ++m) _Pragma("unroll") for (int k = 0; k < 2; ++k) dst[m][k] = *(const LAS bf16x8*)(lds + PG8_SA(b, h) + aoff + m * 2048 + k * 1024); } while (0)
; #define PG8_LDB(dst, b, h) do { _Pragma("unroll") for (int n = 0; n < 2; ++n) _Pragma("unroll") for (int k = 0; k < 2; ++k) dst[n][k] = *(const LAS bf16x8*)(lds + PG8_SB(b, h) + boff + n * 2048 + k * 1024); } while (0)
; #define PG8_MMA(ai, bj, At, Bt) do { __builtin_amdgcn_s_setprio(1); _Pragma("unroll") for (int m = 0; m < NM; ++m) _Pragma("unroll") for (int n = 0; n < 2; ++n) _Pragma("unroll") for (int k = 0; k < 2; ++k) \
;         acc[ai][bj][m][n] = __builtin_amdgcn_mfma_f32_16x16x32_bf16(Bt[n][k], At[m][k], acc[ai][bj][m][n], 0, 0, 0); __builtin_amdgcn_s_setprio(0); } while (0)
; #define PG8_WAIT_V(n) asm volatile("s_waitcnt vmcnt(" #n ")" ::: "memory")
; #define PG8_WAIT_L(n) asm volatile("s_waitcnt lgkmcnt(" #n ")" ::: "memory")
; #define PG8_BAR __builtin_amdgcn_s_barrier()
; #define PG8_SCHED __builtin_amdgcn_sched_barrier(0)
;     ...
;             PG8_LDB(B0, 0, 0); PG8_LDB(B1, 0, 1); PG8_SCHED; PG8_LDA(At, 0, 0); PG8_STAGE(PG8_SA(1, 1), a1 + hstepA, voffA);
;             PG8_WAIT_V(8); PG8_WAIT_L(0); PG8_BAR; PG8_MMA(0, 0, At, B0); PG8_MMA(0, 1, At, B1); PG8_BAR; PG8_SCHED;
;             PG8_LDA(At, 0, 1); PG8_STAGE(PG8_SB(0, 0), b2, voffB); PG8_STAGE(PG8_SB(0, 1), b2 + hstepB, voffB); PG8_STAGE(PG8_SA(0, 0), a2, voffA);
;             PG8_WAIT_V(8); PG8_WAIT_L(0); PG8_BAR; PG8_MMA(1, 0, At, B0); PG8_MMA(1, 1, At, B1); PG8_BAR; PG8_SCHED;
;             PG8_LDB(B0, 1, 0); PG8_LDB(B1, 1, 1); PG8_SCHED; PG8_LDA(At, 1, 0); PG8_STAGE(PG8_SA(0, 1), a2 + hstepA, voffA);
;             PG8_WAIT_V(8); PG8_WAIT_L(0); PG8_BAR; PG8_MMA(0, 0, At, B0); PG8_MMA(0, 1, At, B1); PG8_BAR; PG8_SCHED;
;             PG8_LDA(At, 1, 1); PG8_STAGE(PG8_SB(1, 0), b3, voffB); PG8_STAGE(PG8_SB(1, 1), b3 + hstepB, voffB); PG8_STAGE(PG8_SA(1, 0), a3, voffA);
;             PG8_WAIT_V(8); PG8_WAIT_L(0); PG8_BAR; PG8_MMA(1, 0, At, B0); PG8_MMA(1, 1, At, B1); PG8_BAR; PG8_SCHED;
.LBB0_1650:
	v_add_u32_e32 v102, s21, v166
	v_add_u32_e32 v126, s31, v166
	ds_read_b128 v[90:93], v102
	ds_read_b128 v[94:97], v102 offset:1024
	ds_read_b128 v[98:101], v102 offset:2048
	ds_read_b128 v[102:105], v102 offset:3072
	ds_read_b128 v[114:117], v126
	ds_read_b128 v[118:121], v126 offset:1024
	ds_read_b128 v[122:125], v126 offset:2048
	ds_read_b128 v[126:129], v126 offset:3072
	s_add_u32 s22, s8, 0xfffa0080
	s_addc_u32 s23, s9, -1
	s_cmp_eq_u32 s59, 28
	s_cselect_b32 s25, s17, s23
	s_cselect_b32 s24, s16, s22
	s_cselect_b32 s23, s2, s58
	s_cselect_b32 s22, s3, s15
	v_lshl_add_u64 v[164:165], s[8:9], 0, v[148:149]
	s_add_i32 m0, s35, 0xc000
	ds_read_b128 v[130:133], v167
	ds_read_b128 v[134:137], v167 offset:1024
	ds_read_b128 v[138:141], v167 offset:2048
	ds_read_b128 v[152:155], v167 offset:3072
	ds_read_b128 v[156:159], v167 offset:4096
	ds_read_b128 v[160:163], v167 offset:5120
	global_load_lds_dwordx4 v[164:165], off
	v_lshl_add_u64 v[164:165], s[8:9], 0, v[150:151]
	s_add_i32 m0, s35, 0xe000
	s_nop 0
	s_and_b64 vcc, exec, s[10:11]
	s_cbranch_vccz .Lnm3o_skip0
	global_load_lds_dwordx4 v[164:165], off
	s_waitcnt vmcnt(8)
	s_branch .Lnm3o_done0
.Lnm3o_skip0:
	s_waitcnt vmcnt(6)
.Lnm3o_done0:
	s_waitcnt lgkmcnt(0)
	s_barrier
	s_setprio 1
	s_waitcnt lgkmcnt(0)
	v_mfma_f32_16x16x32_bf16 v[110:113], v[90:93], v[130:133], v[110:113]
	v_mfma_f32_16x16x32_bf16 v[106:109], v[98:101], v[130:133], v[106:109]
	v_mfma_f32_16x16x32_bf16 v[78:81], v[90:93], v[138:141], v[78:81]
	v_mfma_f32_16x16x32_bf16 v[74:77], v[98:101], v[138:141], v[74:77]
	v_mfma_f32_16x16x32_bf16 v[62:65], v[90:93], v[156:159], v[62:65]
	v_mfma_f32_16x16x32_bf16 v[58:61], v[98:101], v[156:159], v[58:61]
	v_mfma_f32_16x16x32_bf16 v[110:113], v[94:97], v[134:137], v[110:113]
	v_mfma_f32_16x16x32_bf16 v[106:109], v[102:105], v[134:137], v[106:109]
	v_mfma_f32_16x16x32_bf16 v[78:81], v[94:97], v[152:155], v[78:81]
	v_mfma_f32_16x16x32_bf16 v[74:77], v[102:105], v[152:155], v[74:77]
	v_mfma_f32_16x16x32_bf16 v[62:65], v[94:97], v[160:163], v[62:65]
	v_mfma_f32_16x16x32_bf16 v[58:61], v[102:105], v[160:163], v[58:61]
	s_setprio 0
	s_setprio 1
	v_mfma_f32_16x16x32_bf16 v[86:89], v[114:117], v[130:133], v[86:89]
	v_mfma_f32_16x16x32_bf16 v[82:85], v[122:125], v[130:133], v[82:85]
	v_mfma_f32_16x16x32_bf16 v[70:73], v[114:117], v[138:141], v[70:73]
	v_mfma_f32_16x16x32_bf16 v[66:69], v[122:125], v[138:141], v[66:69]
	v_mfma_f32_16x16x32_bf16 v[54:57], v[114:117], v[156:159], v[54:57]
	v_mfma_f32_16x16x32_bf16 v[50:53], v[122:125], v[156:159], v[50:53]
	v_mfma_f32_16x16x32_bf16 v[86:89], v[118:121], v[134:137], v[86:89]
	v_mfma_f32_16x16x32_bf16 v[82:85], v[126:129], v[134:137], v[82:85]
	v_mfma_f32_16x16x32_bf16 v[70:73], v[118:121], v[152:155], v[70:73]
	v_mfma_f32_16x16x32_bf16 v[66:69], v[126:129], v[152:155], v[66:69]
	v_mfma_f32_16x16x32_bf16 v[54:57], v[118:121], v[160:163], v[54:57]
	v_mfma_f32_16x16x32_bf16 v[50:53], v[126:129], v[160:163], v[50:53]
	s_setprio 0
	s_barrier
	s_mov_b32 m0, s29
	v_lshl_add_u64 v[164:165], s[22:23], 0, v[0:1]
	s_add_u32 s62, s22, 0x80000
	ds_read_b128 v[130:133], v167 offset:16384
	ds_read_b128 v[134:137], v167 offset:17408
	ds_read_b128 v[138:141], v167 offset:18432
	ds_read_b128 v[152:155], v167 offset:19456
	ds_read_b128 v[156:159], v167 offset:20480
	ds_read_b128 v[160:163], v167 offset:21504
	global_load_lds_dwordx4 v[164:165], off
	v_lshl_add_u64 v[168:169], s[22:23], 0, v[146:147]
	s_mov_b32 m0, s30
	s_addc_u32 s63, s23, 0
	global_load_lds_dwordx4 v[168:169], off
	v_lshl_add_u64 v[170:171], s[62:63], 0, v[0:1]
	s_mov_b32 m0, s33
	v_lshl_add_u64 v[172:173], s[24:25], 0, v[144:145]
	global_load_lds_dwordx4 v[170:171], off
	v_lshl_add_u64 v[170:171], s[62:63], 0, v[146:147]
	s_mov_b32 m0, s34
	s_nop 0
	global_load_lds_dwordx4 v[170:171], off
	v_lshl_add_u64 v[170:171], s[24:25], 0, v[142:143]
	s_mov_b32 m0, s35
	s_nop 0
	global_load_lds_dwordx4 v[170:171], off
	s_mov_b32 m0, s36
	s_nop 0
	s_and_b64 vcc, exec, s[10:11]
	s_cbranch_vccz .Lnm3o_skip1
	global_load_lds_dwordx4 v[172:173], off
	s_waitcnt vmcnt(8)
	s_branch .Lnm3o_done1

; #define PG8_STAGE(bufoff, gbase, voff) do { _Pragma("unroll") for (int _i = 0; _i < 2; ++_i) \
;         __builtin_amdgcn_global_load_lds((const unsigned*)((const char*)(gbase) + (voff)[_i]), (LAS unsigned*)(lds + (bufoff) + ldsw + _i * 8192), 16, 0, 0); } while (0)
; #define PG8_LDA(dst, b, h) do { _Pragma("unroll") for (int m = 0; m < NM; ++m) _Pragma("unroll") for (int k = 0; k < 2; ++k) dst[m][k] = *(const LAS bf16x8*)(lds + PG8_SA(b, h) + aoff + m * 2048 + k * 1024); } while (0)
; #define PG8_LDB(dst, b, h) do { _Pragma("unroll") for (int n = 0; n < 2; ++n) _Pragma("unroll") for (int k = 0; k < 2; ++k) dst[n][k] = *(const LAS bf16x8*)(lds + PG8_SB(b, h) + boff + n * 2048 + k * 1024); } while (0)
; #define PG8_MMA(ai, bj, At, Bt) do { __builtin_amdgcn_s_setprio(1); _Pragma("unroll") for (int m = 0; m < NM; ++m) _Pragma("unroll") for (int n = 0; n < 2; ++n) _Pragma("unroll") for (int k = 0; k < 2; ++k) \
;         acc[ai][bj][m][n] = __builtin_amdgcn_mfma_f32_16x16x32_bf16(Bt[n][k], At[m][k], acc[ai][bj][m][n], 0, 0, 0); __builtin_amdgcn_s_setprio(0); } while (0)
; #define PG8_WAIT_V(n) asm volatile("s_waitcnt vmcnt(" #n ")" ::: "memory")
; #define PG8_WAIT_L(n) asm volatile("s_waitcnt lgkmcnt(" #n ")" ::: "memory")
; #define PG8_BAR __builtin_amdgcn_s_barrier()
; #define PG8_SCHED __builtin_amdgcn_sched_barrier(0)
;     ...
;             PG8_WAIT_V(8); PG8_WAIT_L(0); PG8_BAR; PG8_MMA(1, 0, At, B0); PG8_MMA(1, 1, At, B1); PG8_BAR; PG8_SCHED;
;             PG8_LDB(B0, 1, 0); PG8_LDB(B1, 1, 1); PG8_SCHED; PG8_LDA(At, 1, 0); PG8_STAGE(PG8_SA(0, 1), a2 + hstepA, voffA);
.Lnm3o_done1:
	s_waitcnt lgkmcnt(0)
	s_barrier
	s_setprio 1
	s_waitcnt lgkmcnt(0)
	v_mfma_f32_16x16x32_bf16 v[46:49], v[90:93], v[130:133], v[46:49]
	v_mfma_f32_16x16x32_bf16 v[42:45], v[98:101], v[130:133], v[42:45]
	v_mfma_f32_16x16x32_bf16 v[30:33], v[90:93], v[138:141], v[30:33]
	v_mfma_f32_16x16x32_bf16 v[26:29], v[98:101], v[138:141], v[26:29]
	v_mfma_f32_16x16x32_bf16 v[14:17], v[90:93], v[156:159], v[14:17]
	v_mfma_f32_16x16x32_bf16 v[10:13], v[98:101], v[156:159], v[10:13]
	v_mfma_f32_16x16x32_bf16 v[46:49], v[94:97], v[134:137], v[46:49]
	v_mfma_f32_16x16x32_bf16 v[42:45], v[102:105], v[134:137], v[42:45]
	v_mfma_f32_16x16x32_bf16 v[30:33], v[94:97], v[152:155], v[30:33]
	v_mfma_f32_16x16x32_bf16 v[26:29], v[102:105], v[152:155], v[26:29]
	v_mfma_f32_16x16x32_bf16 v[14:17], v[94:97], v[160:163], v[14:17]
	v_mfma_f32_16x16x32_bf16 v[10:13], v[102:105], v[160:163], v[10:13]
	s_setprio 0
	s_setprio 1
	v_mfma_f32_16x16x32_bf16 v[38:41], v[114:117], v[130:133], v[38:41]
	v_mfma_f32_16x16x32_bf16 v[34:37], v[122:125], v[130:133], v[34:37]
	v_mfma_f32_16x16x32_bf16 v[22:25], v[114:117], v[138:141], v[22:25]
	v_mfma_f32_16x16x32_bf16 v[18:21], v[122:125], v[138:141], v[18:21]
	v_mfma_f32_16x16x32_bf16 v[6:9], v[114:117], v[156:159], v[6:9]
	v_mfma_f32_16x16x32_bf16 v[2:5], v[122:125], v[156:159], v[2:5]
	v_mfma_f32_16x16x32_bf16 v[38:41], v[118:121], v[134:137], v[38:41]
	v_mfma_f32_16x16x32_bf16 v[34:37], v[126:129], v[134:137], v[34:37]
	v_mfma_f32_16x16x32_bf16 v[22:25], v[118:121], v[152:155], v[22:25]
	v_mfma_f32_16x16x32_bf16 v[18:21], v[126:129], v[152:155], v[18:21]
	v_mfma_f32_16x16x32_bf16 v[6:9], v[118:121], v[160:163], v[6:9]
	v_mfma_f32_16x16x32_bf16 v[2:5], v[126:129], v[160:163], v[2:5]
	s_setprio 0
	s_barrier
	v_add_u32_e32 v102, s40, v166
	v_add_u32_e32 v126, s45, v166
	ds_read_b128 v[90:93], v102
	ds_read_b128 v[94:97], v102 offset:1024
	ds_read_b128 v[98:101], v102 offset:2048
	ds_read_b128 v[102:105], v102 offset:3072
	ds_read_b128 v[114:117], v126
	ds_read_b128 v[118:121], v126 offset:1024
	ds_read_b128 v[122:125], v126 offset:2048
	ds_read_b128 v[126:129], v126 offset:3072
	s_add_u32 s24, s24, 0x60000
	s_addc_u32 s25, s25, 0
	s_mov_b32 m0, s37
	v_lshl_add_u64 v[174:175], s[24:25], 0, v[142:143]
	ds_read_b128 v[130:133], v167 offset:32768
	ds_read_b128 v[134:137], v167 offset:33792
	ds_read_b128 v[138:141], v167 offset:34816
	ds_read_b128 v[152:155], v167 offset:35840
	ds_read_b128 v[156:159], v167 offset:36864
	ds_read_b128 v[160:163], v167 offset:37888
	global_load_lds_dwordx4 v[174:175], off
	v_lshl_add_u64 v[174:175], s[24:25], 0, v[144:145]
	s_mov_b32 m0, s38
	s_nop 0
	s_and_b64 vcc, exec, s[10:11]
	s_cbranch_vccz .Lnm3o_skip2
	global_load_lds_dwordx4 v[174:175], off
	s_waitcnt vmcnt(8)
	s_branch .Lnm3o_done2

; #define PG8_STAGE(bufoff, gbase, voff) do { _Pragma("unroll") for (int _i = 0; _i < 2; ++_i) \
;         __builtin_amdgcn_global_load_lds((const unsigned*)((const char*)(gbase) + (voff)[_i]), (LAS unsigned*)(lds + (bufoff) + ldsw + _i * 8192), 16, 0, 0); } while (0)
; #define PG8_LDA(dst, b, h) do { _Pragma("unroll") for (int m = 0; m < NM; ++m) _Pragma("unroll") for (int k = 0; k < 2; ++k) dst[m][k] = *(const LAS bf16x8*)(lds + PG8_SA(b, h) + aoff + m * 2048 + k * 1024); } while (0)
; #define PG8_MMA(ai, bj, At, Bt) do { __builtin_amdgcn_s_setprio(1); _Pragma("unroll") for (int m = 0; m < NM; ++m) _Pragma("unroll") for (int n = 0; n < 2; ++n) _Pragma("unroll") for (int k = 0; k < 2; ++k) \
;         acc[ai][bj][m][n] = __builtin_amdgcn_mfma_f32_16x16x32_bf16(Bt[n][k], At[m][k], acc[ai][bj][m][n], 0, 0, 0); __builtin_amdgcn_s_setprio(0); } while (0)
; #define PG8_WAIT_V(n) asm volatile("s_waitcnt vmcnt(" #n ")" ::: "memory")
; #define PG8_WAIT_L(n) asm volatile("s_waitcnt lgkmcnt(" #n ")" ::: "memory")
; #define PG8_BAR __builtin_amdgcn_s_barrier()
; #define PG8_SCHED __builtin_amdgcn_sched_barrier(0)
;     ...
;             PG8_WAIT_V(8); PG8_WAIT_L(0); PG8_BAR; PG8_MMA(0, 0, At, B0); PG8_MMA(0, 1, At, B1); PG8_BAR; PG8_SCHED;
;             PG8_LDA(At, 1, 1); PG8_STAGE(PG8_SB(1, 0), b3, voffB); PG8_STAGE(PG8_SB(1, 1), b3 + hstepB, voffB); PG8_STAGE(PG8_SA(1, 0), a3, voffA);
.Lnm3o_done2:
	s_waitcnt lgkmcnt(0)
	s_barrier
	s_setprio 1
	s_waitcnt lgkmcnt(0)
	v_mfma_f32_16x16x32_bf16 v[110:113], v[90:93], v[130:133], v[110:113]
	v_mfma_f32_16x16x32_bf16 v[106:109], v[98:101], v[130:133], v[106:109]
	v_mfma_f32_16x16x32_bf16 v[78:81], v[90:93], v[138:141], v[78:81]
	v_mfma_f32_16x16x32_bf16 v[74:77], v[98:101], v[138:141], v[74:77]
	v_mfma_f32_16x16x32_bf16 v[62:65], v[90:93], v[156:159], v[62:65]
	v_mfma_f32_16x16x32_bf16 v[58:61], v[98:101], v[156:159], v[58:61]
	v_mfma_f32_16x16x32_bf16 v[110:113], v[94:97], v[134:137], v[110:113]
	v_mfma_f32_16x16x32_bf16 v[106:109], v[102:105], v[134:137], v[106:109]
	v_mfma_f32_16x16x32_bf16 v[78:81], v[94:97], v[152:155], v[78:81]
	v_mfma_f32_16x16x32_bf16 v[74:77], v[102:105], v[152:155], v[74:77]
	v_mfma_f32_16x16x32_bf16 v[62:65], v[94:97], v[160:163], v[62:65]
	v_mfma_f32_16x16x32_bf16 v[58:61], v[102:105], v[160:163], v[58:61]
	s_setprio 0
	s_setprio 1
	v_mfma_f32_16x16x32_bf16 v[86:89], v[114:117], v[130:133], v[86:89]
	v_mfma_f32_16x16x32_bf16 v[82:85], v[122:125], v[130:133], v[82:85]
	v_mfma_f32_16x16x32_bf16 v[70:73], v[114:117], v[138:141], v[70:73]
	v_mfma_f32_16x16x32_bf16 v[66:69], v[122:125], v[138:141], v[66:69]
	v_mfma_f32_16x16x32_bf16 v[54:57], v[114:117], v[156:159], v[54:57]
	v_mfma_f32_16x16x32_bf16 v[50:53], v[122:125], v[156:159], v[50:53]
	v_mfma_f32_16x16x32_bf16 v[86:89], v[118:121], v[134:137], v[86:89]
	v_mfma_f32_16x16x32_bf16 v[82:85], v[126:129], v[134:137], v[82:85]
	v_mfma_f32_16x16x32_bf16 v[70:73], v[118:121], v[152:155], v[70:73]
	v_mfma_f32_16x16x32_bf16 v[66:69], v[126:129], v[152:155], v[66:69]
	v_mfma_f32_16x16x32_bf16 v[54:57], v[118:121], v[160:163], v[54:57]
	v_mfma_f32_16x16x32_bf16 v[50:53], v[126:129], v[160:163], v[50:53]
	s_setprio 0
	s_barrier
	s_mov_b32 m0, s41
	v_lshl_add_u64 v[164:165], v[164:165], 0, s[66:67]
	s_add_u32 s22, s22, 0x80080
	ds_read_b128 v[130:133], v167 offset:49152
	ds_read_b128 v[134:137], v167 offset:50176
	ds_read_b128 v[138:141], v167 offset:51200
	ds_read_b128 v[152:155], v167 offset:52224
	ds_read_b128 v[156:159], v167 offset:53248
	ds_read_b128 v[160:163], v167 offset:54272
	global_load_lds_dwordx4 v[164:165], off
	v_lshl_add_u64 v[164:165], v[168:169], 0, s[66:67]
	s_mov_b32 m0, s42
	s_addc_u32 s23, s23, 0
	global_load_lds_dwordx4 v[164:165], off
	v_lshl_add_u64 v[164:165], s[22:23], 0, v[0:1]
	s_mov_b32 m0, s46
	s_nop 0
	global_load_lds_dwordx4 v[164:165], off
	v_lshl_add_u64 v[164:165], s[22:23], 0, v[146:147]
	s_mov_b32 m0, s47
	s_nop 0
	global_load_lds_dwordx4 v[164:165], off
	v_lshl_add_u64 v[164:165], v[170:171], 0, s[66:67]
	s_mov_b32 m0, s43
	s_nop 0
	global_load_lds_dwordx4 v[164:165], off
	v_lshl_add_u64 v[164:165], v[172:173], 0, s[66:67]
	s_mov_b32 m0, s44
	s_nop 0
	s_and_b64 vcc, exec, s[10:11]
	s_cbranch_vccz .Lnm3o_skip3
	global_load_lds_dwordx4 v[164:165], off
	s_waitcnt vmcnt(8)
	s_branch .Lnm3o_done3

; #define PG8_STAGE(bufoff, gbase, voff) do { _Pragma("unroll") for (int _i = 0; _i < 2; ++_i) \
;         __builtin_amdgcn_global_load_lds((const unsigned*)((const char*)(gbase) + (voff)[_i]), (LAS unsigned*)(lds + (bufoff) + ldsw + _i * 8192), 16, 0, 0); } while (0)
; #define PG8_LDA(dst, b, h) do { _Pragma("unroll") for (int m = 0; m < NM; ++m) _Pragma("unroll") for (int k = 0; k < 2; ++k) dst[m][k] = *(const LAS bf16x8*)(lds + PG8_SA(b, h) + aoff + m * 2048 + k * 1024); } while (0)
; #define PG8_LDB(dst, b, h) do { _Pragma("unroll") for (int n = 0; n < 2; ++n) _Pragma("unroll") for (int k = 0; k < 2; ++k) dst[n][k] = *(const LAS bf16x8*)(lds + PG8_SB(b, h) + boff + n * 2048 + k * 1024); } while (0)
; #define PG8_WAIT_V(n) asm volatile("s_waitcnt vmcnt(" #n ")" ::: "memory")
; #define PG8_WAIT_L(n) asm volatile("s_waitcnt lgkmcnt(" #n ")" ::: "memory")
; #define PG8_BAR __builtin_amdgcn_s_barrier()
;     ...
;             PG8_WAIT_V(8); PG8_WAIT_L(0); PG8_BAR; PG8_MMA(1, 0, At, B0); PG8_MMA(1, 1, At, B1); PG8_BAR; PG8_SCHED;
;             } else {
;             PG8_LDB(B0, 0, 0); PG8_SCHED; PG8_LDA(At, 0, 0); PG8_STAGE(PG8_SA(1, 1), a1 + hstepA, voffA);
;             PG8_WAIT_L(8); PG8_BAR; PG8_WAIT_L(0); PG8_MMA(0, 0, At, B0); PG8_BAR; PG8_SCHED;
;             PG8_LDB(B1, 0, 1); PG8_STAGE(PG8_SB(0, 0), b2, voffB);
;             PG8_BAR; PG8_WAIT_L(0); PG8_MMA(0, 1, At, B1); PG8_BAR;
;             PG8_LDA(At, 0, 1); PG8_STAGE(PG8_SA(0, 0), a2, voffA);
;             PG8_BAR; PG8_WAIT_L(0); PG8_MMA(1, 0, At, B0); PG8_BAR; PG8_SCHED;
;             PG8_STAGE(PG8_SB(0, 1), b2 + hstepB, voffB);
;             PG8_WAIT_V(6); PG8_BAR; PG8_MMA(1, 1, At, B1); PG8_BAR;
;             PG8_LDB(B0, 1, 0); PG8_SCHED; PG8_LDA(At, 1, 0); PG8_STAGE(PG8_SA(0, 1), a2 + hstepA, voffA);
;             PG8_WAIT_L(8); PG8_BAR; PG8_WAIT_L(0); PG8_MMA(0, 0, At, B0); PG8_BAR; PG8_SCHED;
;             PG8_LDB(B1, 1, 1); PG8_STAGE(PG8_SB(1, 0), b3, voffB);
;             PG8_BAR; PG8_WAIT_L(0); PG8_MMA(0, 1, At, B1); PG8_BAR;
;             PG8_LDA(At, 1, 1); PG8_STAGE(PG8_SA(1, 0), a3, voffA);
;             PG8_BAR; PG8_WAIT_L(0); PG8_MMA(1, 0, At, B0); PG8_BAR; PG8_SCHED;
;             PG8_STAGE(PG8_SB(1, 1), b3 + hstepB, voffB);
;             PG8_WAIT_V(6); PG8_BAR; PG8_MMA(1, 1, At, B1); PG8_BAR;
;             }
;         }
;         if constexpr (ALIGN_EPI) { if (wr == 0) PG8_BAR; }
.Lnm3o_done3:
	s_waitcnt lgkmcnt(0)
	s_barrier
	s_setprio 1
	s_waitcnt lgkmcnt(0)
	v_mfma_f32_16x16x32_bf16 v[46:49], v[90:93], v[130:133], v[46:49]
	v_mfma_f32_16x16x32_bf16 v[42:45], v[98:101], v[130:133], v[42:45]
	v_mfma_f32_16x16x32_bf16 v[30:33], v[90:93], v[138:141], v[30:33]
	v_mfma_f32_16x16x32_bf16 v[26:29], v[98:101], v[138:141], v[26:29]
	v_mfma_f32_16x16x32_bf16 v[14:17], v[90:93], v[156:159], v[14:17]
	v_mfma_f32_16x16x32_bf16 v[10:13], v[98:101], v[156:159], v[10:13]
	v_mfma_f32_16x16x32_bf16 v[46:49], v[94:97], v[134:137], v[46:49]
	v_mfma_f32_16x16x32_bf16 v[42:45], v[102:105], v[134:137], v[42:45]
	v_mfma_f32_16x16x32_bf16 v[30:33], v[94:97], v[152:155], v[30:33]
	v_mfma_f32_16x16x32_bf16 v[26:29], v[102:105], v[152:155], v[26:29]
	v_mfma_f32_16x16x32_bf16 v[14:17], v[94:97], v[160:163], v[14:17]
	v_mfma_f32_16x16x32_bf16 v[10:13], v[102:105], v[160:163], v[10:13]
	s_setprio 0
	s_setprio 1
	v_mfma_f32_16x16x32_bf16 v[38:41], v[114:117], v[130:133], v[38:41]
	v_mfma_f32_16x16x32_bf16 v[34:37], v[122:125], v[130:133], v[34:37]
	v_mfma_f32_16x16x32_bf16 v[22:25], v[114:117], v[138:141], v[22:25]
	v_mfma_f32_16x16x32_bf16 v[18:21], v[122:125], v[138:141], v[18:21]
	v_mfma_f32_16x16x32_bf16 v[6:9], v[114:117], v[156:159], v[6:9]
	v_mfma_f32_16x16x32_bf16 v[2:5], v[122:125], v[156:159], v[2:5]
	v_mfma_f32_16x16x32_bf16 v[38:41], v[118:121], v[134:137], v[38:41]
	v_mfma_f32_16x16x32_bf16 v[34:37], v[126:129], v[134:137], v[34:37]
	v_mfma_f32_16x16x32_bf16 v[22:25], v[118:121], v[152:155], v[22:25]
	v_mfma_f32_16x16x32_bf16 v[18:21], v[126:129], v[152:155], v[18:21]
	v_mfma_f32_16x16x32_bf16 v[6:9], v[118:121], v[160:163], v[6:9]
	v_mfma_f32_16x16x32_bf16 v[2:5], v[126:129], v[160:163], v[2:5]
	s_setprio 0
	s_barrier
	s_add_i32 s59, s59, 2
	s_add_u32 s8, s8, 0x100
	s_addc_u32 s9, s9, 0
	s_add_u32 s15, s15, 0x100
	s_addc_u32 s58, s58, 0
	s_cmp_gt_u32 s59, 29
	s_cbranch_scc0 .LBB0_1650
	s_and_b64 vcc, exec, s[10:11]
	s_cbranch_vccz .LBB0_1653
	s_barrier

; #define PG8_STAGE(bufoff, gbase, voff) do { _Pragma("unroll") for (int _i = 0; _i < 2; ++_i) \
;         __builtin_amdgcn_global_load_lds((const unsigned*)((const char*)(gbase) + (voff)[_i]), (LAS unsigned*)(lds + (bufoff) + ldsw + _i * 8192), 16, 0, 0); } while (0)
; #define PG8_LDA(dst, b, h) do { _Pragma("unroll") for (int m = 0; m < NM; ++m) _Pragma("unroll") for (int k = 0; k < 2; ++k) dst[m][k] = *(const LAS bf16x8*)(lds + PG8_SA(b, h) + aoff + m * 2048 + k * 1024); } while (0)
; #define PG8_LDB(dst, b, h) do { _Pragma("unroll") for (int n = 0; n < 2; ++n) _Pragma("unroll") for (int k = 0; k < 2; ++k) dst[n][k] = *(const LAS bf16x8*)(lds + PG8_SB(b, h) + boff + n * 2048 + k * 1024); } while (0)
; #define PG8_MMA(ai, bj, At, Bt) do { __builtin_amdgcn_s_setprio(1); _Pragma("unroll") for (int m = 0; m < NM; ++m) _Pragma("unroll") for (int n = 0; n < 2; ++n) _Pragma("unroll") for (int k = 0; k < 2; ++k) \
;         acc[ai][bj][m][n] = __builtin_amdgcn_mfma_f32_16x16x32_bf16(Bt[n][k], At[m][k], acc[ai][bj][m][n], 0, 0, 0); __builtin_amdgcn_s_setprio(0); } while (0)
; #define PG8_WAIT_V(n) asm volatile("s_waitcnt vmcnt(" #n ")" ::: "memory")
; #define PG8_WAIT_L(n) asm volatile("s_waitcnt lgkmcnt(" #n ")" ::: "memory")
; #define PG8_BAR __builtin_amdgcn_s_barrier()
; #define PG8_SCHED __builtin_amdgcn_sched_barrier(0)
;     ...
;             PG8_LDB(B0, 0, 0); PG8_LDB(B1, 0, 1); PG8_SCHED; PG8_LDA(At, 0, 0); PG8_STAGE(PG8_SA(1, 1), a1 + hstepA, voffA);
;             PG8_WAIT_V(8); PG8_WAIT_L(0); PG8_BAR; PG8_MMA(0, 0, At, B0); PG8_MMA(0, 1, At, B1); PG8_BAR; PG8_SCHED;
.LBB0_2158:
	v_add_u32_e32 v102, s26, v166
	v_add_u32_e32 v126, s29, v166
	ds_read_b128 v[90:93], v102
	ds_read_b128 v[94:97], v102 offset:1024
	ds_read_b128 v[98:101], v102 offset:2048
	ds_read_b128 v[102:105], v102 offset:3072
	ds_read_b128 v[114:117], v126
	ds_read_b128 v[118:121], v126 offset:1024
	ds_read_b128 v[122:125], v126 offset:2048
	ds_read_b128 v[126:129], v126 offset:3072
	s_add_u32 s16, s14, 0x100
	s_addc_u32 s17, s15, 0
	s_cmpk_eq_i32 s60, 0x54
	s_cselect_b32 s21, s7, s17
	s_cselect_b32 s20, s6, s16
	s_cselect_b32 s19, s13, s3
	s_cselect_b32 s18, s12, s2
	v_lshl_add_u64 v[164:165], s[14:15], 0, v[148:149]
	s_add_i32 m0, s34, 0xc000
	ds_read_b128 v[130:133], v167
	ds_read_b128 v[134:137], v167 offset:1024
	ds_read_b128 v[138:141], v167 offset:2048
	ds_read_b128 v[152:155], v167 offset:3072
	ds_read_b128 v[156:159], v167 offset:4096
	ds_read_b128 v[160:163], v167 offset:5120
	global_load_lds_dwordx4 v[164:165], off
	v_lshl_add_u64 v[164:165], s[14:15], 0, v[150:151]
	s_add_i32 m0, s34, 0xe000
	s_nop 0
	s_and_b64 vcc, exec, s[8:9]
	s_cbranch_vccz .Lnm3d_skip0
	global_load_lds_dwordx4 v[164:165], off
	s_waitcnt vmcnt(8)
	s_branch .Lnm3d_done0

; #define PG8_STAGE(bufoff, gbase, voff) do { _Pragma("unroll") for (int _i = 0; _i < 2; ++_i) \
;         __builtin_amdgcn_global_load_lds((const unsigned*)((const char*)(gbase) + (voff)[_i]), (LAS unsigned*)(lds + (bufoff) + ldsw + _i * 8192), 16, 0, 0); } while (0)
; #define PG8_LDA(dst, b, h) do { _Pragma("unroll") for (int m = 0; m < NM; ++m) _Pragma("unroll") for (int k = 0; k < 2; ++k) dst[m][k] = *(const LAS bf16x8*)(lds + PG8_SA(b, h) + aoff + m * 2048 + k * 1024); } while (0)
; #define PG8_MMA(ai, bj, At, Bt) do { __builtin_amdgcn_s_setprio(1); _Pragma("unroll") for (int m = 0; m < NM; ++m) _Pragma("unroll") for (int n = 0; n < 2; ++n) _Pragma("unroll") for (int k = 0; k < 2; ++k) \
;         acc[ai][bj][m][n] = __builtin_amdgcn_mfma_f32_16x16x32_bf16(Bt[n][k], At[m][k], acc[ai][bj][m][n], 0, 0, 0); __builtin_amdgcn_s_setprio(0); } while (0)
; #define PG8_WAIT_V(n) asm volatile("s_waitcnt vmcnt(" #n ")" ::: "memory")
; #define PG8_WAIT_L(n) asm volatile("s_waitcnt lgkmcnt(" #n ")" ::: "memory")
; #define PG8_BAR __builtin_amdgcn_s_barrier()
; #define PG8_SCHED __builtin_amdgcn_sched_barrier(0)
;     ...
;             PG8_WAIT_V(8); PG8_WAIT_L(0); PG8_BAR; PG8_MMA(0, 0, At, B0); PG8_MMA(0, 1, At, B1); PG8_BAR; PG8_SCHED;
;             PG8_LDA(At, 0, 1); PG8_STAGE(PG8_SB(0, 0), b2, voffB); PG8_STAGE(PG8_SB(0, 1), b2 + hstepB, voffB); PG8_STAGE(PG8_SA(0, 0), a2, voffA);
.Lnm3d_done0:
	s_waitcnt lgkmcnt(0)
	s_barrier
	s_setprio 1
	s_waitcnt lgkmcnt(0)
	v_mfma_f32_16x16x32_bf16 v[110:113], v[90:93], v[130:133], v[110:113]
	v_mfma_f32_16x16x32_bf16 v[106:109], v[98:101], v[130:133], v[106:109]
	v_mfma_f32_16x16x32_bf16 v[78:81], v[90:93], v[138:141], v[78:81]
	v_mfma_f32_16x16x32_bf16 v[74:77], v[98:101], v[138:141], v[74:77]
	v_mfma_f32_16x16x32_bf16 v[62:65], v[90:93], v[156:159], v[62:65]
	v_mfma_f32_16x16x32_bf16 v[58:61], v[98:101], v[156:159], v[58:61]
	v_mfma_f32_16x16x32_bf16 v[110:113], v[94:97], v[134:137], v[110:113]
	v_mfma_f32_16x16x32_bf16 v[106:109], v[102:105], v[134:137], v[106:109]
	v_mfma_f32_16x16x32_bf16 v[78:81], v[94:97], v[152:155], v[78:81]
	v_mfma_f32_16x16x32_bf16 v[74:77], v[102:105], v[152:155], v[74:77]
	v_mfma_f32_16x16x32_bf16 v[62:65], v[94:97], v[160:163], v[62:65]
	v_mfma_f32_16x16x32_bf16 v[58:61], v[102:105], v[160:163], v[58:61]
	s_setprio 0
	s_setprio 1
	v_mfma_f32_16x16x32_bf16 v[86:89], v[114:117], v[130:133], v[86:89]
	v_mfma_f32_16x16x32_bf16 v[82:85], v[122:125], v[130:133], v[82:85]
	v_mfma_f32_16x16x32_bf16 v[70:73], v[114:117], v[138:141], v[70:73]
	v_mfma_f32_16x16x32_bf16 v[66:69], v[122:125], v[138:141], v[66:69]
	v_mfma_f32_16x16x32_bf16 v[54:57], v[114:117], v[156:159], v[54:57]
	v_mfma_f32_16x16x32_bf16 v[50:53], v[122:125], v[156:159], v[50:53]
	v_mfma_f32_16x16x32_bf16 v[86:89], v[118:121], v[134:137], v[86:89]
	v_mfma_f32_16x16x32_bf16 v[82:85], v[126:129], v[134:137], v[82:85]
	v_mfma_f32_16x16x32_bf16 v[70:73], v[118:121], v[152:155], v[70:73]
	v_mfma_f32_16x16x32_bf16 v[66:69], v[126:129], v[152:155], v[66:69]
	v_mfma_f32_16x16x32_bf16 v[54:57], v[118:121], v[160:163], v[54:57]
	v_mfma_f32_16x16x32_bf16 v[50:53], v[126:129], v[160:163], v[50:53]
	s_setprio 0
	s_barrier
	s_mov_b32 m0, s27
	v_lshl_add_u64 v[164:165], s[18:19], 0, v[0:1]
	s_add_u32 s14, s18, 0x160000
	ds_read_b128 v[130:133], v167 offset:16384
	ds_read_b128 v[134:137], v167 offset:17408
	ds_read_b128 v[138:141], v167 offset:18432
	ds_read_b128 v[152:155], v167 offset:19456
	ds_read_b128 v[156:159], v167 offset:20480
	ds_read_b128 v[160:163], v167 offset:21504
	global_load_lds_dwordx4 v[164:165], off
	v_lshl_add_u64 v[168:169], s[18:19], 0, v[146:147]
	s_mov_b32 m0, s28
	s_addc_u32 s15, s19, 0
	global_load_lds_dwordx4 v[168:169], off
	v_lshl_add_u64 v[170:171], s[14:15], 0, v[0:1]
	s_mov_b32 m0, s30
	v_lshl_add_u64 v[172:173], s[20:21], 0, v[144:145]
	global_load_lds_dwordx4 v[170:171], off
	v_lshl_add_u64 v[170:171], s[14:15], 0, v[146:147]
	s_mov_b32 m0, s31
	s_nop 0
	global_load_lds_dwordx4 v[170:171], off
	v_lshl_add_u64 v[170:171], s[20:21], 0, v[142:143]
	s_mov_b32 m0, s34
	s_nop 0
	global_load_lds_dwordx4 v[170:171], off
	s_mov_b32 m0, s35
	s_nop 0
	s_and_b64 vcc, exec, s[8:9]
	s_cbranch_vccz .Lnm3d_skip1
	global_load_lds_dwordx4 v[172:173], off
	s_waitcnt vmcnt(8)
	s_branch .Lnm3d_done1

; #define PG8_STAGE(bufoff, gbase, voff) do { _Pragma("unroll") for (int _i = 0; _i < 2; ++_i) \
;         __builtin_amdgcn_global_load_lds((const unsigned*)((const char*)(gbase) + (voff)[_i]), (LAS unsigned*)(lds + (bufoff) + ldsw + _i * 8192), 16, 0, 0); } while (0)
; #define PG8_LDA(dst, b, h) do { _Pragma("unroll") for (int m = 0; m < NM; ++m) _Pragma("unroll") for (int k = 0; k < 2; ++k) dst[m][k] = *(const LAS bf16x8*)(lds + PG8_SA(b, h) + aoff + m * 2048 + k * 1024); } while (0)
; #define PG8_LDB(dst, b, h) do { _Pragma("unroll") for (int n = 0; n < 2; ++n) _Pragma("unroll") for (int k = 0; k < 2; ++k) dst[n][k] = *(const LAS bf16x8*)(lds + PG8_SB(b, h) + boff + n * 2048 + k * 1024); } while (0)
; #define PG8_MMA(ai, bj, At, Bt) do { __builtin_amdgcn_s_setprio(1); _Pragma("unroll") for (int m = 0; m < NM; ++m) _Pragma("unroll") for (int n = 0; n < 2; ++n) _Pragma("unroll") for (int k = 0; k < 2; ++k) \
;         acc[ai][bj][m][n] = __builtin_amdgcn_mfma_f32_16x16x32_bf16(Bt[n][k], At[m][k], acc[ai][bj][m][n], 0, 0, 0); __builtin_amdgcn_s_setprio(0); } while (0)
; #define PG8_WAIT_V(n) asm volatile("s_waitcnt vmcnt(" #n ")" ::: "memory")
; #define PG8_WAIT_L(n) asm volatile("s_waitcnt lgkmcnt(" #n ")" ::: "memory")
; #define PG8_BAR __builtin_amdgcn_s_barrier()
; #define PG8_SCHED __builtin_amdgcn_sched_barrier(0)
;     ...
;             PG8_WAIT_V(8); PG8_WAIT_L(0); PG8_BAR; PG8_MMA(1, 0, At, B0); PG8_MMA(1, 1, At, B1); PG8_BAR; PG8_SCHED;
;             PG8_LDB(B0, 1, 0); PG8_LDB(B1, 1, 1); PG8_SCHED; PG8_LDA(At, 1, 0); PG8_STAGE(PG8_SA(0, 1), a2 + hstepA, voffA);
.Lnm3d_done1:
	s_waitcnt lgkmcnt(0)
	s_barrier
	s_setprio 1
	s_waitcnt lgkmcnt(0)
	v_mfma_f32_16x16x32_bf16 v[46:49], v[90:93], v[130:133], v[46:49]
	v_mfma_f32_16x16x32_bf16 v[42:45], v[98:101], v[130:133], v[42:45]
	v_mfma_f32_16x16x32_bf16 v[30:33], v[90:93], v[138:141], v[30:33]
	v_mfma_f32_16x16x32_bf16 v[26:29], v[98:101], v[138:141], v[26:29]
	v_mfma_f32_16x16x32_bf16 v[14:17], v[90:93], v[156:159], v[14:17]
	v_mfma_f32_16x16x32_bf16 v[10:13], v[98:101], v[156:159], v[10:13]
	v_mfma_f32_16x16x32_bf16 v[46:49], v[94:97], v[134:137], v[46:49]
	v_mfma_f32_16x16x32_bf16 v[42:45], v[102:105], v[134:137], v[42:45]
	v_mfma_f32_16x16x32_bf16 v[30:33], v[94:97], v[152:155], v[30:33]
	v_mfma_f32_16x16x32_bf16 v[26:29], v[102:105], v[152:155], v[26:29]
	v_mfma_f32_16x16x32_bf16 v[14:17], v[94:97], v[160:163], v[14:17]
	v_mfma_f32_16x16x32_bf16 v[10:13], v[102:105], v[160:163], v[10:13]
	s_setprio 0
	s_setprio 1
	v_mfma_f32_16x16x32_bf16 v[38:41], v[114:117], v[130:133], v[38:41]
	v_mfma_f32_16x16x32_bf16 v[34:37], v[122:125], v[130:133], v[34:37]
	v_mfma_f32_16x16x32_bf16 v[22:25], v[114:117], v[138:141], v[22:25]
	v_mfma_f32_16x16x32_bf16 v[18:21], v[122:125], v[138:141], v[18:21]
	v_mfma_f32_16x16x32_bf16 v[6:9], v[114:117], v[156:159], v[6:9]
	v_mfma_f32_16x16x32_bf16 v[2:5], v[122:125], v[156:159], v[2:5]
	v_mfma_f32_16x16x32_bf16 v[38:41], v[118:121], v[134:137], v[38:41]
	v_mfma_f32_16x16x32_bf16 v[34:37], v[126:129], v[134:137], v[34:37]
	v_mfma_f32_16x16x32_bf16 v[22:25], v[118:121], v[152:155], v[22:25]
	v_mfma_f32_16x16x32_bf16 v[18:21], v[126:129], v[152:155], v[18:21]
	v_mfma_f32_16x16x32_bf16 v[6:9], v[118:121], v[160:163], v[6:9]
	v_mfma_f32_16x16x32_bf16 v[2:5], v[126:129], v[160:163], v[2:5]
	s_setprio 0
	s_barrier
	v_add_u32_e32 v102, s38, v166
	v_add_u32_e32 v126, s45, v166
	ds_read_b128 v[90:93], v102
	ds_read_b128 v[94:97], v102 offset:1024
	ds_read_b128 v[98:101], v102 offset:2048
	ds_read_b128 v[102:105], v102 offset:3072
	ds_read_b128 v[114:117], v126
	ds_read_b128 v[118:121], v126 offset:1024
	ds_read_b128 v[122:125], v126 offset:2048
	ds_read_b128 v[126:129], v126 offset:3072
	s_add_u32 s14, s20, 0x108000
	s_addc_u32 s15, s21, 0
	s_mov_b32 m0, s36
	v_lshl_add_u64 v[174:175], s[14:15], 0, v[142:143]
	ds_read_b128 v[130:133], v167 offset:32768
	ds_read_b128 v[134:137], v167 offset:33792
	ds_read_b128 v[138:141], v167 offset:34816
	ds_read_b128 v[152:155], v167 offset:35840
	ds_read_b128 v[156:159], v167 offset:36864
	ds_read_b128 v[160:163], v167 offset:37888
	global_load_lds_dwordx4 v[174:175], off
	v_lshl_add_u64 v[174:175], s[14:15], 0, v[144:145]
	s_mov_b32 m0, s37
	s_nop 0
	s_and_b64 vcc, exec, s[8:9]
	s_cbranch_vccz .Lnm3d_skip2
	global_load_lds_dwordx4 v[174:175], off
	s_waitcnt vmcnt(8)
	s_branch .Lnm3d_done2

; #define PG8_STAGE(bufoff, gbase, voff) do { _Pragma("unroll") for (int _i = 0; _i < 2; ++_i) \
;         __builtin_amdgcn_global_load_lds((const unsigned*)((const char*)(gbase) + (voff)[_i]), (LAS unsigned*)(lds + (bufoff) + ldsw + _i * 8192), 16, 0, 0); } while (0)
; #define PG8_LDA(dst, b, h) do { _Pragma("unroll") for (int m = 0; m < NM; ++m) _Pragma("unroll") for (int k = 0; k < 2; ++k) dst[m][k] = *(const LAS bf16x8*)(lds + PG8_SA(b, h) + aoff + m * 2048 + k * 1024); } while (0)
; #define PG8_MMA(ai, bj, At, Bt) do { __builtin_amdgcn_s_setprio(1); _Pragma("unroll") for (int m = 0; m < NM; ++m) _Pragma("unroll") for (int n = 0; n < 2; ++n) _Pragma("unroll") for (int k = 0; k < 2; ++k) \
;         acc[ai][bj][m][n] = __builtin_amdgcn_mfma_f32_16x16x32_bf16(Bt[n][k], At[m][k], acc[ai][bj][m][n], 0, 0, 0); __builtin_amdgcn_s_setprio(0); } while (0)
; #define PG8_WAIT_V(n) asm volatile("s_waitcnt vmcnt(" #n ")" ::: "memory")
; #define PG8_WAIT_L(n) asm volatile("s_waitcnt lgkmcnt(" #n ")" ::: "memory")
; #define PG8_BAR __builtin_amdgcn_s_barrier()
; #define PG8_SCHED __builtin_amdgcn_sched_barrier(0)
;     ...
;             PG8_WAIT_V(8); PG8_WAIT_L(0); PG8_BAR; PG8_MMA(0, 0, At, B0); PG8_MMA(0, 1, At, B1); PG8_BAR; PG8_SCHED;
;             PG8_LDA(At, 1, 1); PG8_STAGE(PG8_SB(1, 0), b3, voffB); PG8_STAGE(PG8_SB(1, 1), b3 + hstepB, voffB); PG8_STAGE(PG8_SA(1, 0), a3, voffA);
.Lnm3d_done2:
	s_waitcnt lgkmcnt(0)
	s_barrier
	s_setprio 1
	s_waitcnt lgkmcnt(0)
	v_mfma_f32_16x16x32_bf16 v[110:113], v[90:93], v[130:133], v[110:113]
	v_mfma_f32_16x16x32_bf16 v[106:109], v[98:101], v[130:133], v[106:109]
	v_mfma_f32_16x16x32_bf16 v[78:81], v[90:93], v[138:141], v[78:81]
	v_mfma_f32_16x16x32_bf16 v[74:77], v[98:101], v[138:141], v[74:77]
	v_mfma_f32_16x16x32_bf16 v[62:65], v[90:93], v[156:159], v[62:65]
	v_mfma_f32_16x16x32_bf16 v[58:61], v[98:101], v[156:159], v[58:61]
	v_mfma_f32_16x16x32_bf16 v[110:113], v[94:97], v[134:137], v[110:113]
	v_mfma_f32_16x16x32_bf16 v[106:109], v[102:105], v[134:137], v[106:109]
	v_mfma_f32_16x16x32_bf16 v[78:81], v[94:97], v[152:155], v[78:81]
	v_mfma_f32_16x16x32_bf16 v[74:77], v[102:105], v[152:155], v[74:77]
	v_mfma_f32_16x16x32_bf16 v[62:65], v[94:97], v[160:163], v[62:65]
	v_mfma_f32_16x16x32_bf16 v[58:61], v[102:105], v[160:163], v[58:61]
	s_setprio 0
	s_setprio 1
	v_mfma_f32_16x16x32_bf16 v[86:89], v[114:117], v[130:133], v[86:89]
	v_mfma_f32_16x16x32_bf16 v[82:85], v[122:125], v[130:133], v[82:85]
	v_mfma_f32_16x16x32_bf16 v[70:73], v[114:117], v[138:141], v[70:73]
	v_mfma_f32_16x16x32_bf16 v[66:69], v[122:125], v[138:141], v[66:69]
	v_mfma_f32_16x16x32_bf16 v[54:57], v[114:117], v[156:159], v[54:57]
	v_mfma_f32_16x16x32_bf16 v[50:53], v[122:125], v[156:159], v[50:53]
	v_mfma_f32_16x16x32_bf16 v[86:89], v[118:121], v[134:137], v[86:89]
	v_mfma_f32_16x16x32_bf16 v[82:85], v[126:129], v[134:137], v[82:85]
	v_mfma_f32_16x16x32_bf16 v[70:73], v[118:121], v[152:155], v[70:73]
	v_mfma_f32_16x16x32_bf16 v[66:69], v[126:129], v[152:155], v[66:69]
	v_mfma_f32_16x16x32_bf16 v[54:57], v[118:121], v[160:163], v[54:57]
	v_mfma_f32_16x16x32_bf16 v[50:53], v[126:129], v[160:163], v[50:53]
	s_setprio 0
	s_barrier
	s_mov_b32 m0, s41
	v_lshl_add_u64 v[164:165], v[164:165], 0, s[66:67]
	s_add_u32 s14, s18, 0x160080
	ds_read_b128 v[130:133], v167 offset:49152
	ds_read_b128 v[134:137], v167 offset:50176
	ds_read_b128 v[138:141], v167 offset:51200
	ds_read_b128 v[152:155], v167 offset:52224
	ds_read_b128 v[156:159], v167 offset:53248
	ds_read_b128 v[160:163], v167 offset:54272
	global_load_lds_dwordx4 v[164:165], off
	v_lshl_add_u64 v[164:165], v[168:169], 0, s[66:67]
	s_mov_b32 m0, s42
	s_addc_u32 s15, s19, 0
	global_load_lds_dwordx4 v[164:165], off
	v_lshl_add_u64 v[164:165], s[14:15], 0, v[0:1]
	s_mov_b32 m0, s46
	s_nop 0
	global_load_lds_dwordx4 v[164:165], off
	v_lshl_add_u64 v[164:165], s[14:15], 0, v[146:147]
	s_mov_b32 m0, s47
	s_nop 0
	global_load_lds_dwordx4 v[164:165], off
	v_lshl_add_u64 v[164:165], v[170:171], 0, s[66:67]
	s_mov_b32 m0, s43
	s_nop 0
	global_load_lds_dwordx4 v[164:165], off
	v_lshl_add_u64 v[164:165], v[172:173], 0, s[66:67]
	s_mov_b32 m0, s44
	s_nop 0
	s_and_b64 vcc, exec, s[8:9]
	s_cbranch_vccz .Lnm3d_skip3
	global_load_lds_dwordx4 v[164:165], off
	s_waitcnt vmcnt(8)
	s_branch .Lnm3d_done3

; #define PG8_STAGE(bufoff, gbase, voff) do { _Pragma("unroll") for (int _i = 0; _i < 2; ++_i) \
;         __builtin_amdgcn_global_load_lds((const unsigned*)((const char*)(gbase) + (voff)[_i]), (LAS unsigned*)(lds + (bufoff) + ldsw + _i * 8192), 16, 0, 0); } while (0)
; #define PG8_LDA(dst, b, h) do { _Pragma("unroll") for (int m = 0; m < NM; ++m) _Pragma("unroll") for (int k = 0; k < 2; ++k) dst[m][k] = *(const LAS bf16x8*)(lds + PG8_SA(b, h) + aoff + m * 2048 + k * 1024); } while (0)
; #define PG8_LDB(dst, b, h) do { _Pragma("unroll") for (int n = 0; n < 2; ++n) _Pragma("unroll") for (int k = 0; k < 2; ++k) dst[n][k] = *(const LAS bf16x8*)(lds + PG8_SB(b, h) + boff + n * 2048 + k * 1024); } while (0)
; #define PG8_WAIT_V(n) asm volatile("s_waitcnt vmcnt(" #n ")" ::: "memory")
; #define PG8_WAIT_L(n) asm volatile("s_waitcnt lgkmcnt(" #n ")" ::: "memory")
; #define PG8_BAR __builtin_amdgcn_s_barrier()
;     ...
;             PG8_WAIT_V(8); PG8_WAIT_L(0); PG8_BAR; PG8_MMA(1, 0, At, B0); PG8_MMA(1, 1, At, B1); PG8_BAR; PG8_SCHED;
;             } else {
;             PG8_LDB(B0, 0, 0); PG8_SCHED; PG8_LDA(At, 0, 0); PG8_STAGE(PG8_SA(1, 1), a1 + hstepA, voffA);
;             PG8_WAIT_L(8); PG8_BAR; PG8_WAIT_L(0); PG8_MMA(0, 0, At, B0); PG8_BAR; PG8_SCHED;
;             PG8_LDB(B1, 0, 1); PG8_STAGE(PG8_SB(0, 0), b2, voffB);
;             PG8_BAR; PG8_WAIT_L(0); PG8_MMA(0, 1, At, B1); PG8_BAR;
;             PG8_LDA(At, 0, 1); PG8_STAGE(PG8_SA(0, 0), a2, voffA);
;             PG8_BAR; PG8_WAIT_L(0); PG8_MMA(1, 0, At, B0); PG8_BAR; PG8_SCHED;
;             PG8_STAGE(PG8_SB(0, 1), b2 + hstepB, voffB);
;             PG8_WAIT_V(6); PG8_BAR; PG8_MMA(1, 1, At, B1); PG8_BAR;
;             PG8_LDB(B0, 1, 0); PG8_SCHED; PG8_LDA(At, 1, 0); PG8_STAGE(PG8_SA(0, 1), a2 + hstepA, voffA);
;             PG8_WAIT_L(8); PG8_BAR; PG8_WAIT_L(0); PG8_MMA(0, 0, At, B0); PG8_BAR; PG8_SCHED;
;             PG8_LDB(B1, 1, 1); PG8_STAGE(PG8_SB(1, 0), b3, voffB);
;             PG8_BAR; PG8_WAIT_L(0); PG8_MMA(0, 1, At, B1); PG8_BAR;
;             PG8_LDA(At, 1, 1); PG8_STAGE(PG8_SA(1, 0), a3, voffA);
;             PG8_BAR; PG8_WAIT_L(0); PG8_MMA(1, 0, At, B0); PG8_BAR; PG8_SCHED;
;             PG8_STAGE(PG8_SB(1, 1), b3 + hstepB, voffB);
;             PG8_WAIT_V(6); PG8_BAR; PG8_MMA(1, 1, At, B1); PG8_BAR;
;             }
;         }
;         if constexpr (ALIGN_EPI) { if (wr == 0) PG8_BAR; }
.Lnm3d_done3:
	s_waitcnt lgkmcnt(0)
	s_barrier
	s_setprio 1
	s_waitcnt lgkmcnt(0)
	v_mfma_f32_16x16x32_bf16 v[46:49], v[90:93], v[130:133], v[46:49]
	v_mfma_f32_16x16x32_bf16 v[42:45], v[98:101], v[130:133], v[42:45]
	v_mfma_f32_16x16x32_bf16 v[30:33], v[90:93], v[138:141], v[30:33]
	v_mfma_f32_16x16x32_bf16 v[26:29], v[98:101], v[138:141], v[26:29]
	v_mfma_f32_16x16x32_bf16 v[14:17], v[90:93], v[156:159], v[14:17]
	v_mfma_f32_16x16x32_bf16 v[10:13], v[98:101], v[156:159], v[10:13]
	v_mfma_f32_16x16x32_bf16 v[46:49], v[94:97], v[134:137], v[46:49]
	v_mfma_f32_16x16x32_bf16 v[42:45], v[102:105], v[134:137], v[42:45]
	v_mfma_f32_16x16x32_bf16 v[30:33], v[94:97], v[152:155], v[30:33]
	v_mfma_f32_16x16x32_bf16 v[26:29], v[102:105], v[152:155], v[26:29]
	v_mfma_f32_16x16x32_bf16 v[14:17], v[94:97], v[160:163], v[14:17]
	v_mfma_f32_16x16x32_bf16 v[10:13], v[102:105], v[160:163], v[10:13]
	s_setprio 0
	s_setprio 1
	v_mfma_f32_16x16x32_bf16 v[38:41], v[114:117], v[130:133], v[38:41]
	v_mfma_f32_16x16x32_bf16 v[34:37], v[122:125], v[130:133], v[34:37]
	v_mfma_f32_16x16x32_bf16 v[22:25], v[114:117], v[138:141], v[22:25]
	v_mfma_f32_16x16x32_bf16 v[18:21], v[122:125], v[138:141], v[18:21]
	v_mfma_f32_16x16x32_bf16 v[6:9], v[114:117], v[156:159], v[6:9]
	v_mfma_f32_16x16x32_bf16 v[2:5], v[122:125], v[156:159], v[2:5]
	v_mfma_f32_16x16x32_bf16 v[38:41], v[118:121], v[134:137], v[38:41]
	v_mfma_f32_16x16x32_bf16 v[34:37], v[126:129], v[134:137], v[34:37]
	v_mfma_f32_16x16x32_bf16 v[22:25], v[118:121], v[152:155], v[22:25]
	v_mfma_f32_16x16x32_bf16 v[18:21], v[126:129], v[152:155], v[18:21]
	v_mfma_f32_16x16x32_bf16 v[6:9], v[118:121], v[160:163], v[6:9]
	v_mfma_f32_16x16x32_bf16 v[2:5], v[126:129], v[160:163], v[2:5]
	s_setprio 0
	s_barrier
	s_add_i32 s60, s60, 2
	s_add_u32 s2, s2, 0x100
	s_addc_u32 s3, s3, 0
	s_cmpk_gt_u32 s60, 0x55
	s_mov_b64 s[14:15], s[16:17]
	s_cbranch_scc0 .LBB0_2158
	s_and_b64 vcc, exec, s[8:9]
	s_cbranch_vccz .LBB0_2161
	s_barrier
